# g1-dilated-attention-bias-mask-block-rewritten-batched-lds-reads
# speedup vs baseline: 1.0044x; 1.0012x over previous
; template <int MODE> ...
;     ...
;             {
;                 bf16x8 ka[4], kc[4];
; #pragma unroll
;                 for (int ds = 0; ds < 4; ++ds) {
;                     ka[ds] = *(const LAS bf16x8*)(kb + r32 * AT_KROW + mp * 128 + (16 * ds + 8 * hi) * 2);
;                     kc[ds] = *(const LAS bf16x8*)(kb + (32 + r32) * AT_KROW + mp * 128 + (16 * ds + 8 * hi) * 2);
;                 }
;                 __builtin_amdgcn_sched_barrier(0);
; #pragma unroll
;                 for (int ds = 0; ds < 4; ++ds) {
;                     s0 = __builtin_amdgcn_mfma_f32_32x32x16_bf16(ka[ds], qf[ds], s0, 0, 0, 0);
;                     s1 = __builtin_amdgcn_mfma_f32_32x32x16_bf16(kc[ds], qf[ds], s1, 0, 0, 0);
;                 }
;             }
;             const int relbase = qi - kv0 - 4 * hi;
;             constexpr int cmax = (MODE == 0) ? 2047 : 128;
;             float mx = -1e30f;
;             bool interior = (kv0 + 63 <= q_lo);
;             if (MODE == 1) interior = interior && (q_lo + 31 - kv0 <= 128);
;             if (interior) {
;                 const LAS float* p = biasL + mp * 2048 + (relbase - 59);
; #pragma unroll
;                 for (int r = 0; r < 16; ++r) {
;                     const int o = 59 - ((r & 3) + 8 * (r >> 2));
;                     s0[r] += p[o]; s1[r] += p[o - 32];
;                     mx = fmaxf(mx, fmaxf(s0[r], s1[r]));
;                 }
;             } else {
;                 const volatile LAS float* bl = (const volatile LAS float*)(biasL + mp * 2048);
;                 float bb0[16], bb1[16];
; #pragma unroll
;                 for (int r = 0; r < 16; ++r) {
;                     const int rel0 = relbase - ((r & 3) + 8 * (r >> 2));
;                     bb0[r] = bl[min(max(rel0, 0), cmax)]; bb1[r] = bl[min(max(rel0 - 32, 0), cmax)];
;                 }
; #pragma unroll
;                 for (int r = 0; r < 16; ++r) {
;                     const int rel0 = relbase - ((r & 3) + 8 * (r >> 2)), rel1 = rel0 - 32;
;                     bool ok0 = rel0 >= 0, ok1 = rel1 >= 0;
;                     if (MODE == 1) { ok0 = ok0 && (rel0 <= 128); ok1 = ok1 && (rel1 <= 128); }
;                     const float t0 = s0[r] + bb0[r], t1 = s1[r] + bb1[r];
;                     s0[r] = ok0 ? t0 : -1e30f; s1[r] = ok1 ? t1 : -1e30f;
;                     mx = fmaxf(mx, fmaxf(s0[r], s1[r]));
;                 }
;             }
.LBB0_439:
	s_mul_i32 s19, s15, 0x8800
	s_add_i32 s42, s19, 0
	s_add_i32 s19, s34, s42
	v_add3_u32 v42, s19, v179, v120
	ds_read_b128 v[34:37], v42
	ds_read_b128 v[132:135], v42 offset:32
	ds_read_b128 v[38:41], v42 offset:8704
	ds_read_b128 v[136:139], v42 offset:8736
	ds_read_b128 v[140:143], v42 offset:64
	ds_read_b128 v[148:151], v42 offset:96
	ds_read_b128 v[152:155], v42 offset:8768
	ds_read_b128 v[156:159], v42 offset:8800
	s_waitcnt lgkmcnt(0)
	v_mfma_f32_32x32x16_bf16 v[50:65], v[34:37], v[66:69], 0
	s_cmp_le_i32 s18, s28
	s_cselect_b64 s[18:19], -1, 0
	s_cmpk_lt_i32 s39, 0x81
	s_cselect_b64 s[48:49], -1, 0
	s_and_b64 s[48:49], s[18:19], s[48:49]
	s_mov_b64 s[18:19], -1
	s_andn2_b64 vcc, exec, s[48:49]
	v_mfma_f32_32x32x16_bf16 v[34:49], v[38:41], v[66:69], 0
	v_mfma_f32_32x32x16_bf16 v[50:65], v[132:135], v[70:73], v[50:65]
	v_mfma_f32_32x32x16_bf16 v[34:49], v[136:139], v[70:73], v[34:49]
	v_mfma_f32_32x32x16_bf16 v[50:65], v[140:143], v[74:77], v[50:65]
	v_mfma_f32_32x32x16_bf16 v[34:49], v[152:155], v[74:77], v[34:49]
	v_mfma_f32_32x32x16_bf16 v[50:65], v[148:151], v[78:81], v[50:65]
	v_mfma_f32_32x32x16_bf16 v[34:49], v[156:159], v[78:81], v[34:49]
	s_cbranch_vccz .Ldil_bias_interior
	v_add_u32_e32 v185, s39, v182
	ds_read2_b32 v[132:133], v183 offset0:58 offset1:59
	ds_read2_b32 v[136:137], v183 offset0:26 offset1:27
	ds_read2_b32 v[134:135], v183 offset0:56 offset1:57
	ds_read2_b32 v[138:139], v183 offset0:24 offset1:25
	ds_read2_b32 v[140:141], v183 offset0:50 offset1:51
	ds_read2_b32 v[142:143], v183 offset0:18 offset1:19
	ds_read2_b32 v[144:145], v183 offset0:48 offset1:49
	ds_read2_b32 v[150:151], v183 offset0:16 offset1:17
	ds_read2_b32 v[148:149], v183 offset0:42 offset1:43
	ds_read2_b32 v[152:153], v183 offset0:10 offset1:11
	ds_read2_b32 v[166:167], v183 offset0:40 offset1:41
	ds_read2_b32 v[168:169], v183 offset0:8 offset1:9
	s_waitcnt lgkmcnt(11)
	v_pk_add_f32 v[132:133], v[50:51], v[132:133] op_sel:[0,1] op_sel_hi:[1,0]
	v_add_u32_e32 v186, 0xffffffe1, v185
	v_add_u32_e32 v187, 0xffffffe0, v185
	v_cmp_gt_u32_e32 vcc, s85, v186
	v_cmp_gt_u32_e64 s[100:101], s85, v187
	s_nop 1
	v_cndmask_b32_e32 v132, v214, v132, vcc
	v_cndmask_b32_e64 v133, v214, v133, s[100:101]
	s_waitcnt lgkmcnt(10)
	v_pk_add_f32 v[136:137], v[34:35], v[136:137] op_sel:[0,1] op_sel_hi:[1,0]
	v_add_u32_e32 v186, 0xffffffc1, v185
	v_add_u32_e32 v187, 0xffffffc0, v185
	v_cmp_gt_u32_e32 vcc, s85, v186
	v_cmp_gt_u32_e64 s[100:101], s85, v187
	s_nop 1
	v_cndmask_b32_e32 v136, v214, v136, vcc
	v_cndmask_b32_e64 v137, v214, v137, s[100:101]
	s_waitcnt lgkmcnt(9)
	v_pk_add_f32 v[134:135], v[52:53], v[134:135] op_sel:[0,1] op_sel_hi:[1,0]
	v_add_u32_e32 v186, 0xffffffdf, v185
	v_add_u32_e32 v187, 0xffffffde, v185
	v_cmp_gt_u32_e32 vcc, s85, v186
	v_cmp_gt_u32_e64 s[100:101], s85, v187
	s_nop 1
	v_cndmask_b32_e32 v134, v214, v134, vcc
	v_cndmask_b32_e64 v135, v214, v135, s[100:101]
	s_waitcnt lgkmcnt(8)
	v_pk_add_f32 v[138:139], v[36:37], v[138:139] op_sel:[0,1] op_sel_hi:[1,0]
	v_add_u32_e32 v186, 0xffffffbf, v185
	v_add_u32_e32 v187, 0xffffffbe, v185
	v_cmp_gt_u32_e32 vcc, s85, v186
	v_cmp_gt_u32_e64 s[100:101], s85, v187
	s_nop 1
	v_cndmask_b32_e32 v138, v214, v138, vcc
	v_cndmask_b32_e64 v139, v214, v139, s[100:101]
	ds_read2_b32 v[170:171], v183 offset0:34 offset1:35
	ds_read2_b32 v[172:173], v183 offset0:2 offset1:3
	ds_read2_b32 v[174:175], v183 offset0:32 offset1:33
	ds_read2_b32 v[176:177], v183 offset0:0 offset1:1
	s_waitcnt lgkmcnt(11)
	v_pk_add_f32 v[140:141], v[54:55], v[140:141] op_sel:[0,1] op_sel_hi:[1,0]
	v_add_u32_e32 v186, 0xffffffd9, v185
	v_add_u32_e32 v187, 0xffffffd8, v185
	v_cmp_gt_u32_e32 vcc, s85, v186
	v_cmp_gt_u32_e64 s[100:101], s85, v187
	s_nop 1
	v_cndmask_b32_e32 v140, v214, v140, vcc
	v_cndmask_b32_e64 v141, v214, v141, s[100:101]
	s_waitcnt lgkmcnt(10)
	v_pk_add_f32 v[142:143], v[38:39], v[142:143] op_sel:[0,1] op_sel_hi:[1,0]
	v_add_u32_e32 v186, 0xffffffb9, v185
	v_add_u32_e32 v187, 0xffffffb8, v185
	v_cmp_gt_u32_e32 vcc, s85, v186
	v_cmp_gt_u32_e64 s[100:101], s85, v187
	s_nop 1
	v_cndmask_b32_e32 v142, v214, v142, vcc
	v_cndmask_b32_e64 v143, v214, v143, s[100:101]
	s_waitcnt lgkmcnt(9)
	v_pk_add_f32 v[144:145], v[56:57], v[144:145] op_sel:[0,1] op_sel_hi:[1,0]
	v_add_u32_e32 v186, 0xffffffd7, v185
	v_add_u32_e32 v187, 0xffffffd6, v185
	v_cmp_gt_u32_e32 vcc, s85, v186
	v_cmp_gt_u32_e64 s[100:101], s85, v187
	s_nop 1
	v_cndmask_b32_e32 v144, v214, v144, vcc
	v_cndmask_b32_e64 v145, v214, v145, s[100:101]
	s_waitcnt lgkmcnt(8)
	v_pk_add_f32 v[150:151], v[40:41], v[150:151] op_sel:[0,1] op_sel_hi:[1,0]
	v_add_u32_e32 v186, 0xffffffb7, v185
	v_add_u32_e32 v187, 0xffffffb6, v185
	v_cmp_gt_u32_e32 vcc, s85, v186
	v_cmp_gt_u32_e64 s[100:101], s85, v187
	s_nop 1
	v_cndmask_b32_e32 v150, v214, v150, vcc
	v_cndmask_b32_e64 v151, v214, v151, s[100:101]
	s_waitcnt lgkmcnt(7)
	v_pk_add_f32 v[148:149], v[58:59], v[148:149] op_sel:[0,1] op_sel_hi:[1,0]
	v_add_u32_e32 v186, 0xffffffd1, v185
	v_add_u32_e32 v187, 0xffffffd0, v185
	v_cmp_gt_u32_e32 vcc, s85, v186
	v_cmp_gt_u32_e64 s[100:101], s85, v187
	s_nop 1
	v_cndmask_b32_e32 v148, v214, v148, vcc
	v_cndmask_b32_e64 v149, v214, v149, s[100:101]
	s_waitcnt lgkmcnt(6)
	v_pk_add_f32 v[152:153], v[42:43], v[152:153] op_sel:[0,1] op_sel_hi:[1,0]
	v_add_u32_e32 v186, 0xffffffb1, v185
	v_add_u32_e32 v187, 0xffffffb0, v185
	v_cmp_gt_u32_e32 vcc, s85, v186
	v_cmp_gt_u32_e64 s[100:101], s85, v187
	s_nop 1
	v_cndmask_b32_e32 v152, v214, v152, vcc
	v_cndmask_b32_e64 v153, v214, v153, s[100:101]
	s_waitcnt lgkmcnt(5)
; #define LAS __attribute__((address_space(3)))
; template <int MODE> ...
;     ...
;             const int relbase = qi - kv0 - 4 * hi;
;             constexpr int cmax = (MODE == 0) ? 2047 : 128;
;             float mx = -1e30f;
;             bool interior = (kv0 + 63 <= q_lo);
;             if (MODE == 1) interior = interior && (q_lo + 31 - kv0 <= 128);
;             if (interior) {
;                 const LAS float* p = biasL + mp * 2048 + (relbase - 59);
; #pragma unroll
;                 for (int r = 0; r < 16; ++r) {
;                     const int o = 59 - ((r & 3) + 8 * (r >> 2));
;                     s0[r] += p[o]; s1[r] += p[o - 32];
;                     mx = fmaxf(mx, fmaxf(s0[r], s1[r]));
;                 }
;             } else {
;                 const volatile LAS float* bl = (const volatile LAS float*)(biasL + mp * 2048);
;                 float bb0[16], bb1[16];
; #pragma unroll
;                 for (int r = 0; r < 16; ++r) {
;                     const int rel0 = relbase - ((r & 3) + 8 * (r >> 2));
;                     bb0[r] = bl[min(max(rel0, 0), cmax)]; bb1[r] = bl[min(max(rel0 - 32, 0), cmax)];
;                 }
; #pragma unroll
;                 for (int r = 0; r < 16; ++r) {
;                     const int rel0 = relbase - ((r & 3) + 8 * (r >> 2)), rel1 = rel0 - 32;
;                     bool ok0 = rel0 >= 0, ok1 = rel1 >= 0;
;                     if (MODE == 1) { ok0 = ok0 && (rel0 <= 128); ok1 = ok1 && (rel1 <= 128); }
;                     const float t0 = s0[r] + bb0[r], t1 = s1[r] + bb1[r];
;                     s0[r] = ok0 ? t0 : -1e30f; s1[r] = ok1 ? t1 : -1e30f;
;                     mx = fmaxf(mx, fmaxf(s0[r], s1[r]));
;                 }
;             }
	v_pk_add_f32 v[166:167], v[60:61], v[166:167] op_sel:[0,1] op_sel_hi:[1,0]
	v_add_u32_e32 v186, 0xffffffcf, v185
	v_add_u32_e32 v187, 0xffffffce, v185
	v_cmp_gt_u32_e32 vcc, s85, v186
	v_cmp_gt_u32_e64 s[100:101], s85, v187
	s_nop 1
	v_cndmask_b32_e32 v166, v214, v166, vcc
	v_cndmask_b32_e64 v167, v214, v167, s[100:101]
	s_waitcnt lgkmcnt(4)
	v_pk_add_f32 v[168:169], v[44:45], v[168:169] op_sel:[0,1] op_sel_hi:[1,0]
	v_add_u32_e32 v186, 0xffffffaf, v185
	v_add_u32_e32 v187, 0xffffffae, v185
	v_cmp_gt_u32_e32 vcc, s85, v186
	v_cmp_gt_u32_e64 s[100:101], s85, v187
	s_nop 1
	v_cndmask_b32_e32 v168, v214, v168, vcc
	v_cndmask_b32_e64 v169, v214, v169, s[100:101]
	s_waitcnt lgkmcnt(3)
	v_pk_add_f32 v[170:171], v[62:63], v[170:171] op_sel:[0,1] op_sel_hi:[1,0]
	v_add_u32_e32 v186, 0xffffffc9, v185
	v_add_u32_e32 v187, 0xffffffc8, v185
	v_cmp_gt_u32_e32 vcc, s85, v186
	v_cmp_gt_u32_e64 s[100:101], s85, v187
	s_nop 1
	v_cndmask_b32_e32 v170, v214, v170, vcc
	v_cndmask_b32_e64 v171, v214, v171, s[100:101]
	s_waitcnt lgkmcnt(2)
	v_pk_add_f32 v[172:173], v[46:47], v[172:173] op_sel:[0,1] op_sel_hi:[1,0]
	v_add_u32_e32 v186, 0xffffffa9, v185
	v_add_u32_e32 v187, 0xffffffa8, v185
	v_cmp_gt_u32_e32 vcc, s85, v186
	v_cmp_gt_u32_e64 s[100:101], s85, v187
	s_nop 1
	v_cndmask_b32_e32 v172, v214, v172, vcc
	v_cndmask_b32_e64 v173, v214, v173, s[100:101]
	s_waitcnt lgkmcnt(1)
	v_pk_add_f32 v[174:175], v[64:65], v[174:175] op_sel:[0,1] op_sel_hi:[1,0]
	v_add_u32_e32 v186, 0xffffffc7, v185
	v_add_u32_e32 v187, 0xffffffc6, v185
	v_cmp_gt_u32_e32 vcc, s85, v186
	v_cmp_gt_u32_e64 s[100:101], s85, v187
	s_nop 1
	v_cndmask_b32_e32 v174, v214, v174, vcc
	v_cndmask_b32_e64 v175, v214, v175, s[100:101]
	s_waitcnt lgkmcnt(0)
	v_pk_add_f32 v[176:177], v[48:49], v[176:177] op_sel:[0,1] op_sel_hi:[1,0]
	v_add_u32_e32 v186, 0xffffffa7, v185
	v_add_u32_e32 v187, 0xffffffa6, v185
	v_cmp_gt_u32_e32 vcc, s85, v186
	v_cmp_gt_u32_e64 s[100:101], s85, v187
	s_nop 1
	v_cndmask_b32_e32 v176, v214, v176, vcc
	v_cndmask_b32_e64 v177, v214, v177, s[100:101]
	v_max_f32_e32 v34, v132, v136
	v_max_f32_e32 v35, v133, v137
	v_max3_f32 v36, v34, s84, v35
	v_max_f32_e32 v34, v134, v138
	v_max_f32_e32 v35, v135, v139
	v_max3_f32 v36, v36, v34, v35
	v_max_f32_e32 v34, v140, v142
	v_max_f32_e32 v35, v141, v143
	v_max3_f32 v36, v36, v34, v35
	v_max_f32_e32 v34, v144, v150
	v_max_f32_e32 v35, v145, v151
	v_max3_f32 v36, v36, v34, v35
	v_max_f32_e32 v34, v148, v152
	v_max_f32_e32 v35, v149, v153
	v_max3_f32 v36, v36, v34, v35
	v_max_f32_e32 v34, v166, v168
	v_max_f32_e32 v35, v167, v169
	v_max3_f32 v36, v36, v34, v35
	v_max_f32_e32 v34, v170, v172
	v_max_f32_e32 v35, v171, v173
	v_max3_f32 v36, v36, v34, v35
	v_max_f32_e32 v34, v174, v176
	v_max_f32_e32 v35, v175, v177
	v_max3_f32 v184, v36, v34, v35
	s_branch .LBB0_443
.Ldil_bias_interior:
	ds_read2_b32 v[132:133], v183 offset0:58 offset1:59
	ds_read2_b32 v[136:137], v183 offset0:26 offset1:27
	ds_read2_b32 v[134:135], v183 offset0:56 offset1:57
	ds_read2_b32 v[138:139], v183 offset0:24 offset1:25
	ds_read2_b32 v[140:141], v183 offset0:50 offset1:51
	ds_read2_b32 v[142:143], v183 offset0:18 offset1:19
	ds_read2_b32 v[144:145], v183 offset0:48 offset1:49
	ds_read2_b32 v[150:151], v183 offset0:16 offset1:17
	ds_read2_b32 v[148:149], v183 offset0:42 offset1:43
	ds_read2_b32 v[152:153], v183 offset0:10 offset1:11
	ds_read2_b32 v[166:167], v183 offset0:40 offset1:41
	ds_read2_b32 v[168:169], v183 offset0:8 offset1:9
	s_waitcnt lgkmcnt(11)
	v_pk_add_f32 v[132:133], v[50:51], v[132:133] op_sel:[0,1] op_sel_hi:[1,0]
	s_waitcnt lgkmcnt(10)
	v_pk_add_f32 v[136:137], v[34:35], v[136:137] op_sel:[0,1] op_sel_hi:[1,0]
	s_waitcnt lgkmcnt(9)
	v_pk_add_f32 v[134:135], v[52:53], v[134:135] op_sel:[0,1] op_sel_hi:[1,0]
	s_waitcnt lgkmcnt(8)
	v_pk_add_f32 v[138:139], v[36:37], v[138:139] op_sel:[0,1] op_sel_hi:[1,0]
	ds_read2_b32 v[170:171], v183 offset0:34 offset1:35
	ds_read2_b32 v[172:173], v183 offset0:2 offset1:3
	ds_read2_b32 v[174:175], v183 offset0:32 offset1:33
	ds_read2_b32 v[176:177], v183 offset0:0 offset1:1
	s_waitcnt lgkmcnt(11)
	v_pk_add_f32 v[140:141], v[54:55], v[140:141] op_sel:[0,1] op_sel_hi:[1,0]
	s_waitcnt lgkmcnt(10)
	v_pk_add_f32 v[142:143], v[38:39], v[142:143] op_sel:[0,1] op_sel_hi:[1,0]
	s_waitcnt lgkmcnt(9)
	v_pk_add_f32 v[144:145], v[56:57], v[144:145] op_sel:[0,1] op_sel_hi:[1,0]
	s_waitcnt lgkmcnt(8)
	v_pk_add_f32 v[150:151], v[40:41], v[150:151] op_sel:[0,1] op_sel_hi:[1,0]
	s_waitcnt lgkmcnt(7)
	v_pk_add_f32 v[148:149], v[58:59], v[148:149] op_sel:[0,1] op_sel_hi:[1,0]
	s_waitcnt lgkmcnt(6)
	v_pk_add_f32 v[152:153], v[42:43], v[152:153] op_sel:[0,1] op_sel_hi:[1,0]
	s_waitcnt lgkmcnt(5)
	v_pk_add_f32 v[166:167], v[60:61], v[166:167] op_sel:[0,1] op_sel_hi:[1,0]
	s_waitcnt lgkmcnt(4)
	v_pk_add_f32 v[168:169], v[44:45], v[168:169] op_sel:[0,1] op_sel_hi:[1,0]
	s_waitcnt lgkmcnt(3)
	v_pk_add_f32 v[170:171], v[62:63], v[170:171] op_sel:[0,1] op_sel_hi:[1,0]
	s_waitcnt lgkmcnt(2)
	v_pk_add_f32 v[172:173], v[46:47], v[172:173] op_sel:[0,1] op_sel_hi:[1,0]
	s_waitcnt lgkmcnt(1)
	v_pk_add_f32 v[174:175], v[64:65], v[174:175] op_sel:[0,1] op_sel_hi:[1,0]
	s_waitcnt lgkmcnt(0)
	v_pk_add_f32 v[176:177], v[48:49], v[176:177] op_sel:[0,1] op_sel_hi:[1,0]
	v_max_f32_e32 v34, v132, v136
	v_max_f32_e32 v35, v133, v137
	v_max3_f32 v36, v34, s84, v35
	v_max_f32_e32 v34, v134, v138
	v_max_f32_e32 v35, v135, v139
	v_max3_f32 v36, v36, v34, v35
	v_max_f32_e32 v34, v140, v142
	v_max_f32_e32 v35, v141, v143
	v_max3_f32 v36, v36, v34, v35
	v_max_f32_e32 v34, v144, v150
	v_max_f32_e32 v35, v145, v151
	v_max3_f32 v36, v36, v34, v35
	v_max_f32_e32 v34, v148, v152
	v_max_f32_e32 v35, v149, v153
	v_max3_f32 v36, v36, v34, v35
	v_max_f32_e32 v34, v166, v168
	v_max_f32_e32 v35, v167, v169
	v_max3_f32 v36, v36, v34, v35
	v_max_f32_e32 v34, v170, v172
	v_max_f32_e32 v35, v171, v173
	v_max3_f32 v36, v36, v34, v35
	v_max_f32_e32 v34, v174, v176
	v_max_f32_e32 v35, v175, v177
	v_max3_f32 v184, v36, v34, v35

; __global__ void __launch_bounds__(NT_, 2) fwd_mega(Args args) {
	.amdhsa_kernel _Z8fwd_mega4Args
		.amdhsa_group_segment_fixed_size 0
		.amdhsa_private_segment_fixed_size 0
		.amdhsa_kernarg_size 520
		.amdhsa_user_sgpr_count 2
		.amdhsa_user_sgpr_dispatch_ptr 0
		.amdhsa_user_sgpr_queue_ptr 0
		.amdhsa_user_sgpr_kernarg_segment_ptr 1
		.amdhsa_user_sgpr_dispatch_id 0
		.amdhsa_user_sgpr_kernarg_preload_length 0
		.amdhsa_user_sgpr_kernarg_preload_offset 0
		.amdhsa_user_sgpr_private_segment_size 0
		.amdhsa_uses_dynamic_stack 0
		.amdhsa_enable_private_segment 0
		.amdhsa_system_sgpr_workgroup_id_x 1
		.amdhsa_system_sgpr_workgroup_id_y 0
		.amdhsa_system_sgpr_workgroup_id_z 0
		.amdhsa_system_sgpr_workgroup_info 0
		.amdhsa_system_vgpr_workitem_id 2
		.amdhsa_next_free_vgpr 256
		.amdhsa_next_free_sgpr 102
		.amdhsa_accum_offset 256
		.amdhsa_reserve_vcc 1
		.amdhsa_float_round_mode_32 0
		.amdhsa_float_round_mode_16_64 0
		.amdhsa_float_denorm_mode_32 3
		.amdhsa_float_denorm_mode_16_64 3
		.amdhsa_dx10_clamp 1
		.amdhsa_ieee_mode 1
		.amdhsa_fp16_overflow 0
		.amdhsa_tg_split 0
		.amdhsa_exception_fp_ieee_invalid_op 0
		.amdhsa_exception_fp_denorm_src 0
		.amdhsa_exception_fp_ieee_div_zero 0
		.amdhsa_exception_fp_ieee_overflow 0
		.amdhsa_exception_fp_ieee_underflow 0
		.amdhsa_exception_fp_ieee_inexact 0
		.amdhsa_exception_int_div_zero 0
	.end_amdhsa_kernel

; __global__ void __launch_bounds__(NT_, 2) fwd_mega(Args args) {
amdhsa.kernels:
  - .agpr_count:     0
    .args:
      - .offset:         0
        .size:           264
        .value_kind:     by_value
      - .offset:         264
        .size:           4
        .value_kind:     hidden_block_count_x
      - .offset:         268
        .size:           4
        .value_kind:     hidden_block_count_y
      - .offset:         272
        .size:           4
        .value_kind:     hidden_block_count_z
      - .offset:         276
        .size:           2
        .value_kind:     hidden_group_size_x
      - .offset:         278
        .size:           2
        .value_kind:     hidden_group_size_y
      - .offset:         280
        .size:           2
        .value_kind:     hidden_group_size_z
      - .offset:         282
        .size:           2
        .value_kind:     hidden_remainder_x
      - .offset:         284
        .size:           2
        .value_kind:     hidden_remainder_y
      - .offset:         286
        .size:           2
        .value_kind:     hidden_remainder_z
      - .offset:         304
        .size:           8
        .value_kind:     hidden_global_offset_x
      - .offset:         312
        .size:           8
        .value_kind:     hidden_global_offset_y
      - .offset:         320
        .size:           8
        .value_kind:     hidden_global_offset_z
      - .offset:         328
        .size:           2
        .value_kind:     hidden_grid_dims
      - .offset:         352
        .size:           8
        .value_kind:     hidden_multigrid_sync_arg
      - .offset:         384
        .size:           4
        .value_kind:     hidden_dynamic_lds_size
    .group_segment_fixed_size: 0
    .kernarg_segment_align: 8
    .kernarg_segment_size: 520
    .language:       OpenCL C
    .language_version:
      - 2
      - 0
    .max_flat_workgroup_size: 512
    .name:           _Z8fwd_mega4Args
    .private_segment_fixed_size: 0
    .sgpr_count:     108
    .sgpr_spill_count: 124
    .symbol:         _Z8fwd_mega4Args.kd
    .uniform_work_group_size: 1
    .uses_dynamic_stack: false
    .vgpr_count:     256
    .vgpr_spill_count: 0
    .wavefront_size: 64
